# S5 scan Toeplitz step loops: next step's Toeplitz fragment prefetched one step ahead (4 loops), stacked on v64
# speedup vs baseline: 1.0007x; 1.0007x over previous
.LBB0_1012:
	s_waitcnt lgkmcnt(0)
	s_barrier
	ds_read_b128 v[106:109], v220 offset:13056
	ds_read_b128 v[126:129], v220 offset:13120
	ds_read_b128 v[102:105], v220
	s_waitcnt vmcnt(6) lgkmcnt(2)
	v_mfma_f32_16x16x32_bf16 v[110:113], v[38:41], v[106:109], 0
	ds_read_b128 v[98:101], v220 offset:4352
	ds_read_b128 v[114:117], v220 offset:4416
	ds_read_b128 v[86:89], v220 offset:8704
	ds_read_b128 v[122:125], v220 offset:8768
	s_waitcnt vmcnt(2)
	v_mfma_f32_16x16x32_bf16 v[118:121], v[54:57], v[106:109], 0
	ds_read_b128 v[106:109], v220 offset:64
	ds_read_b128 v[138:141], v220 offset:13184
	ds_read_b128 v[134:137], v220 offset:128
	s_waitcnt lgkmcnt(7)
	v_mfma_f32_16x16x32_bf16 v[82:85], v[38:41], v[102:105], 0
	ds_read_b128 v[130:133], v220 offset:4480
	ds_read_b128 v[142:145], v220 offset:4544
	ds_read_b128 v[146:149], v220 offset:8896
	v_mfma_f32_16x16x32_bf16 v[110:113], v[42:45], v[126:129], v[110:113]
	s_lshr_b32 s2, s35, 7
	v_lshl_add_u32 v228, s31, 10, v213
	s_mov_b32 s6, 0
	s_waitcnt vmcnt(1)
	v_mfma_f32_16x16x32_bf16 v[118:121], v[58:61], v[126:129], v[118:121]
	ds_read_b128 v[126:129], v220 offset:8832
	s_waitcnt lgkmcnt(6)
	v_mfma_f32_16x16x32_bf16 v[82:85], v[42:45], v[106:109], v[82:85]
	v_mfma_f32_16x16x32_bf16 v[90:93], v[38:41], v[98:101], 0
	v_mfma_f32_16x16x32_bf16 v[94:97], v[38:41], v[86:89], 0
	s_waitcnt lgkmcnt(5)
	v_mfma_f32_16x16x32_bf16 v[150:153], v[46:49], v[138:141], v[110:113]
	s_waitcnt vmcnt(0)
	v_mfma_f32_16x16x32_bf16 v[154:157], v[62:65], v[138:141], v[118:121]
	ds_read_b128 v[138:141], v220 offset:192
	s_waitcnt lgkmcnt(5)
	v_mfma_f32_16x16x32_bf16 v[82:85], v[46:49], v[134:137], v[82:85]
	v_mfma_f32_16x16x32_bf16 v[90:93], v[42:45], v[114:117], v[90:93]
	v_mfma_f32_16x16x32_bf16 v[94:97], v[42:45], v[122:125], v[94:97]
	s_waitcnt lgkmcnt(0)
	v_mfma_f32_16x16x32_bf16 v[110:113], v[50:53], v[138:141], v[82:85]
	s_nop 3
	ds_read_b128 v[82:85], v220 offset:13248
	v_mfma_f32_16x16x32_bf16 v[90:93], v[46:49], v[130:133], v[90:93]
	v_mfma_f32_16x16x32_bf16 v[94:97], v[46:49], v[126:129], v[94:97]
	v_mfma_f32_16x16x32_bf16 v[118:121], v[50:53], v[142:145], v[90:93]
	v_mfma_f32_16x16x32_bf16 v[90:93], v[50:53], v[146:149], v[94:97]
	s_waitcnt lgkmcnt(0)
	v_mfma_f32_16x16x32_bf16 v[94:97], v[50:53], v[82:85], v[150:153]
	v_mfma_f32_16x16x32_bf16 v[82:85], v[22:25], v[82:85], v[154:157]
	ds_read_b128 v[162:165], v227
	ds_read_b128 v[158:161], v227 offset:8448
	s_nop 0
	ds_read_b128 v[154:157], v227 offset:16896
	ds_read_b128 v[150:153], v227 offset:25344
	ds_read_b128 v[230:233], v228
.LBB0_1013:
	s_add_i32 s7, s6, 1
	s_cmp_lt_u32 s6, s2
	s_cselect_b32 s14, s7, s6
	s_lshl_b32 s15, s14, 7
	s_lshl_b32 s14, s14, 6
	v_add3_u32 v228, v226, s14, v210
	s_sub_i32 s15, s34, s15
	v_or_b32_e32 v229, s15, v186
	v_lshl_add_u32 v246, v229, 4, s3
	ds_read_b128 v[242:245], v246
	s_waitcnt lgkmcnt(1)
	v_mfma_f32_16x16x32_bf16 v[110:113], v[230:233], v[162:165], v[110:113]
	ds_read_b128 v[162:165], v228
	s_cmp_eq_u32 s6, s2
	s_mov_b32 s6, s7
	v_mfma_f32_16x16x32_bf16 v[118:121], v[230:233], v[158:161], v[118:121]
	ds_read_b128 v[158:161], v228 offset:8448
	ds_read_b128 v[234:237], v228 offset:16896
	ds_read_b128 v[238:241], v228 offset:25344
	v_mfma_f32_16x16x32_bf16 v[90:93], v[230:233], v[154:157], v[90:93]
	s_waitcnt lgkmcnt(1)
	v_mov_b32_e32 v154, v234
	v_mov_b32_e32 v155, v235
	v_mov_b32_e32 v156, v236
	v_mfma_f32_16x16x32_bf16 v[94:97], v[230:233], v[150:153], v[94:97]
	s_waitcnt lgkmcnt(0)
	v_mov_b64_e32 v[150:151], v[238:239]
	v_mov_b64_e32 v[152:153], v[240:241]
	v_mov_b32_e32 v157, v237
	v_mov_b64_e32 v[230:231], v[242:243]
	v_mov_b64_e32 v[232:233], v[244:245]
	s_cbranch_scc0 .LBB0_1013
	v_mfma_f32_16x16x32_bf16 v[102:105], v[54:57], v[102:105], 0
	v_mul_f32_e64 v156, v118, s24
	v_mul_f32_e64 v157, v119, s24
	v_pk_mul_f32 v[152:153], v[110:111], s[24:25] op_sel_hi:[1,0]
	v_pk_mul_f32 v[154:155], v[120:121], s[24:25] op_sel_hi:[1,0]
	v_mfma_f32_16x16x32_bf16 v[98:101], v[54:57], v[98:101], 0
	v_fma_f32 v152, v110, v152, 1.0
	v_fma_f32 v153, v111, v153, 1.0
	v_pk_mul_f32 v[150:151], v[112:113], s[24:25] op_sel_hi:[1,0]
	v_pk_mul_f32 v[152:153], v[110:111], v[152:153]
	v_mfma_f32_16x16x32_bf16 v[102:105], v[58:61], v[106:109], v[102:105]
	v_fma_f32 v106, v118, v156, 1.0
	v_fma_f32 v107, v119, v157, 1.0
	v_pk_fma_f32 v[154:155], v[120:121], v[154:155], 1.0 op_sel_hi:[1,1,0]
	v_pk_mul_f32 v[106:107], v[118:119], v[106:107]
	v_mfma_f32_16x16x32_bf16 v[98:101], v[58:61], v[114:117], v[98:101]
	v_mul_f32_e32 v106, 0xc0135761, v106
	v_mul_f32_e32 v108, 0xc0135761, v152
	v_exp_f32_e32 v115, v106
	v_mfma_f32_16x16x32_bf16 v[86:89], v[54:57], v[86:89], 0
	v_mul_f32_e32 v106, 0xc0135761, v153
	v_pk_fma_f32 v[150:151], v[112:113], v[150:151], 1.0 op_sel_hi:[1,1,0]
	v_pk_mul_f32 v[154:155], v[120:121], v[154:155]
	v_exp_f32_e32 v114, v108
	v_exp_f32_e32 v116, v106
	v_mfma_f32_16x16x32_bf16 v[102:105], v[62:65], v[134:137], v[102:105]
	v_mul_f32_e32 v106, 0xc0135761, v107
	v_pk_mul_f32 v[150:151], v[112:113], v[150:151]
	v_exp_f32_e32 v117, v106
	v_mfma_f32_16x16x32_bf16 v[106:109], v[62:65], v[130:133], v[98:101]
	s_lshl_b32 s6, s31, 5
	s_sub_i32 s2, 15, s31
	s_nop 0
	v_mul_f32_e32 v98, 0xc0135761, v154
	v_mfma_f32_16x16x32_bf16 v[86:89], v[58:61], v[122:125], v[86:89]
	v_mul_f32_e32 v122, 0xc0135761, v150
	v_exp_f32_e32 v123, v98
	v_mul_f32_e32 v98, 0xc0135761, v151
	v_mul_f32_e32 v125, 0xc0135761, v155
	v_exp_f32_e32 v122, v122
	v_exp_f32_e32 v124, v98
	v_exp_f32_e32 v125, v125
	v_mfma_f32_16x16x32_bf16 v[98:101], v[22:25], v[138:141], v[102:105]
	s_nop 2
	v_add_f32_e32 v102, 1.0, v114
	v_rcp_f32_e32 v114, v102
	v_mfma_f32_16x16x32_bf16 v[102:105], v[22:25], v[142:145], v[106:109]
	s_nop 2
	v_add_f32_e32 v107, 1.0, v116
	v_add_f32_e32 v106, 1.0, v115
	v_rcp_f32_e32 v115, v107
	v_add_f32_e32 v107, 1.0, v117
	v_add_f32_e32 v109, 1.0, v123
	v_rcp_f32_e32 v106, v106
	v_add_f32_e32 v108, 1.0, v122
	v_rcp_f32_e32 v116, v109
	v_add_f32_e32 v109, 1.0, v124
	v_add_f32_e32 v117, 1.0, v125
	v_rcp_f32_e32 v107, v107
	v_rcp_f32_e32 v108, v108
	v_rcp_f32_e32 v109, v109
	v_rcp_f32_e32 v117, v117
	v_pk_mul_f32 v[110:111], v[110:111], v[114:115]
	v_pk_mul_f32 v[106:107], v[118:119], v[106:107]
	v_pk_mul_f32 v[108:109], v[112:113], v[108:109]
	v_pk_mul_f32 v[112:113], v[120:121], v[116:117]
	v_cvt_pk_bf16_f32 v110, v110, v111
	v_cvt_pk_bf16_f32 v111, v108, v109
	v_cvt_pk_bf16_f32 v106, v106, v107
	v_add3_u32 v114, v214, s6, v210
	v_cvt_pk_bf16_f32 v107, v112, v113
	ds_write_b64 v114, v[110:111]
	ds_write_b64 v114, v[106:107] offset:8448
	v_pk_mul_f32 v[106:107], v[92:93], s[24:25] op_sel_hi:[1,0]
	v_pk_mul_f32 v[110:111], v[96:97], s[24:25] op_sel_hi:[1,0]
	v_pk_fma_f32 v[106:107], v[92:93], v[106:107], 1.0 op_sel_hi:[1,1,0]
	v_pk_mul_f32 v[112:113], v[94:95], s[24:25] op_sel_hi:[1,0]
	v_pk_mul_f32 v[108:109], v[90:91], s[24:25] op_sel_hi:[1,0]
	v_pk_mul_f32 v[106:107], v[92:93], v[106:107]
	v_pk_fma_f32 v[110:111], v[96:97], v[110:111], 1.0 op_sel_hi:[1,1,0]
	v_pk_fma_f32 v[112:113], v[94:95], v[112:113], 1.0 op_sel_hi:[1,1,0]
	v_pk_fma_f32 v[108:109], v[90:91], v[108:109], 1.0 op_sel_hi:[1,1,0]
	v_pk_mul_f32 v[110:111], v[96:97], v[110:111]
	v_pk_mul_f32 v[112:113], v[94:95], v[112:113]
	v_mul_f32_e32 v106, 0xc0135761, v106
	v_pk_mul_f32 v[108:109], v[90:91], v[108:109]
	v_mul_f32_e32 v112, 0xc0135761, v112
	v_exp_f32_e32 v115, v106
	v_mul_f32_e32 v106, 0xc0135761, v110
	v_mul_f32_e32 v108, 0xc0135761, v108
	v_exp_f32_e32 v112, v112
	v_mul_f32_e32 v109, 0xc0135761, v109
	v_exp_f32_e32 v116, v106
	v_mul_f32_e32 v106, 0xc0135761, v107
	v_exp_f32_e32 v108, v108
	v_exp_f32_e32 v109, v109
	v_mul_f32_e32 v113, 0xc0135761, v113
	v_exp_f32_e32 v117, v106
	v_mul_f32_e32 v106, 0xc0135761, v111
	v_exp_f32_e32 v113, v113
	v_exp_f32_e32 v118, v106
	v_mfma_f32_16x16x32_bf16 v[86:89], v[62:65], v[126:129], v[86:89]
	v_add_f32_e32 v107, 1.0, v112
	v_add_f32_e32 v111, 1.0, v116
	v_add_f32_e32 v106, 1.0, v108
	v_rcp_f32_e32 v108, v107
	v_add_f32_e32 v107, 1.0, v109
	v_add_f32_e32 v110, 1.0, v115
	v_rcp_f32_e32 v112, v111
	v_add_f32_e32 v111, 1.0, v117
	v_rcp_f32_e32 v106, v106
	v_rcp_f32_e32 v107, v107
	v_add_f32_e32 v109, 1.0, v113
	v_rcp_f32_e32 v110, v110
	v_rcp_f32_e32 v111, v111
	v_add_f32_e32 v113, 1.0, v118
	v_mfma_f32_16x16x32_bf16 v[86:89], v[22:25], v[146:149], v[86:89]
	v_rcp_f32_e32 v113, v113
	v_rcp_f32_e32 v109, v109
	s_ashr_i32 s6, s2, 1
	v_pk_mul_f32 v[92:93], v[92:93], v[110:111]
	v_pk_mul_f32 v[90:91], v[90:91], v[106:107]
	s_cmp_gt_i32 s6, -1
	v_pk_mul_f32 v[96:97], v[96:97], v[112:113]
	v_pk_mul_f32 v[94:95], v[94:95], v[108:109]
	v_cvt_pk_bf16_f32 v90, v90, v91
	v_cvt_pk_bf16_f32 v91, v92, v93
	s_nop 0
	v_cvt_pk_bf16_f32 v92, v94, v95
	v_cvt_pk_bf16_f32 v93, v96, v97
	ds_write_b64 v114, v[90:91] offset:16896
	ds_write_b64 v114, v[92:93] offset:25344
	s_cbranch_scc0 .LBB0_1017
	ds_read_b128 v[110:113], v227
	ds_read_b128 v[106:109], v227 offset:8448
	ds_read_b128 v[94:97], v227 offset:16896
	ds_read_b128 v[90:93], v227 offset:25344
	v_lshl_add_u32 v114, s2, 10, v213
	s_lshl_b32 s7, s2, 6
	s_mov_b32 s31, 0
	ds_read_b128 v[116:119], v114
.LBB0_1016:
	s_add_i32 s14, s31, 1
	s_cmp_lt_i32 s31, s6
	s_cselect_b32 s15, s14, s31
	s_lshl_b32 s16, s15, 7
	s_lshl_b32 s15, s15, 6
	v_add3_u32 v114, v226, s15, v210
	s_sub_i32 s16, s7, s16
	v_or_b32_e32 v115, s16, v186
	v_lshl_add_u32 v246, v115, 4, s3
	ds_read_b128 v[242:245], v246
	s_waitcnt lgkmcnt(1)
	v_mfma_f32_16x16x32_bf16 v[98:101], v[116:119], v[110:113], v[98:101]
	ds_read_b128 v[110:113], v114
	s_cmp_lg_u32 s31, s6
	s_mov_b32 s31, s14
	v_mfma_f32_16x16x32_bf16 v[102:105], v[116:119], v[106:109], v[102:105]
	ds_read_b128 v[106:109], v114 offset:8448
	ds_read_b128 v[120:123], v114 offset:16896
	ds_read_b128 v[124:127], v114 offset:25344
	v_mfma_f32_16x16x32_bf16 v[86:89], v[116:119], v[94:97], v[86:89]
	s_waitcnt lgkmcnt(1)
	v_mov_b32_e32 v94, v120
	v_mov_b32_e32 v95, v121
	v_mov_b32_e32 v96, v122
	v_mfma_f32_16x16x32_bf16 v[82:85], v[116:119], v[90:93], v[82:85]
	s_waitcnt lgkmcnt(0)
	v_mov_b64_e32 v[90:91], v[124:125]
	v_mov_b64_e32 v[92:93], v[126:127]
	v_mov_b32_e32 v97, v123
	v_mov_b64_e32 v[116:117], v[242:243]
	v_mov_b64_e32 v[118:119], v[244:245]
	s_cbranch_scc1 .LBB0_1016

.LBB0_1023:
	s_ashr_i32 s9, s8, 31
	s_mul_i32 s7, s8, 0x88000
	s_mul_hi_i32 s6, s8, 0x88000
	s_add_u32 s7, s4, s7
	s_addc_u32 s10, s5, s6
	s_add_u32 s6, s7, 0x80000
	s_addc_u32 s7, s10, 0
	v_lshl_add_u64 v[128:129], s[6:7], 0, v[122:123]
	s_movk_i32 s10, 0x2000
	global_load_dwordx4 v[38:41], v122, s[6:7]
	global_load_dwordx4 v[46:49], v124, s[6:7]
	v_add_co_u32_e32 v2, vcc, s10, v128
	v_lshl_add_u64 v[132:133], s[6:7], 0, v[124:125]
	s_mov_b64 s[6:7], 0x6000
	v_addc_co_u32_e32 v3, vcc, 0, v129, vcc
	v_lshl_add_u64 v[134:135], v[128:129], 0, s[6:7]
	s_movk_i32 s6, 0x6000
	global_load_dwordx4 v[42:45], v[2:3], off
	v_add_co_u32_e32 v2, vcc, s6, v128
	s_lshl_b64 s[6:7], s[8:9], 14
	v_lshl_add_u64 v[10:11], v[116:117], 0, s[6:7]
	v_addc_co_u32_e32 v3, vcc, 0, v129, vcc
	v_lshl_add_u64 v[6:7], v[10:11], 0, v[126:127]
	global_load_dwordx4 v[50:53], v[2:3], off
	s_nop 0
	global_load_dwordx4 v[2:5], v[6:7], off
	s_nop 0
	global_load_dwordx4 v[6:9], v[6:7], off offset:16
	v_readfirstlane_b32 s46, v0
	s_lshr_b32 s10, s46, 6
	s_lshl_b64 s[28:29], s[8:9], 16
	s_lshl_b64 s[6:7], s[10:11], 10
	s_mov_b64 s[14:15], 0x2000
	v_lshl_add_u64 v[130:131], v[128:129], 0, s[14:15]
	s_add_i32 s14, s10, 8
	s_mov_b32 s15, s11
	s_lshl_b64 s[14:15], s[14:15], 10
	s_sub_i32 s26, 15, s10
	s_ashr_i32 s27, s26, 31
	v_lshl_or_b32 v90, s8, 6, v186
	v_ashrrev_i32_e32 v91, 31, v90
	v_lshl_add_u64 v[90:91], v[90:91], 3, s[12:13]
	v_readlane_b32 s72, v254, 10
	v_readlane_b32 s78, v254, 16
	v_readlane_b32 s79, v254, 17
	v_readlane_b32 s80, v254, 18
	v_readlane_b32 s81, v254, 19
	s_mov_b64 s[58:59], s[78:79]
	v_readlane_b32 s82, v254, 20
	v_readlane_b32 s83, v254, 21
	v_readlane_b32 s84, v254, 22
	v_readlane_b32 s85, v254, 23
	v_readlane_b32 s86, v254, 24
	v_readlane_b32 s87, v254, 25
	s_mov_b64 s[60:61], s[80:81]
	s_mov_b32 s45, 0
	v_lshl_add_u32 v155, s10, 10, v143
	v_readlane_b32 s73, v254, 11
	v_readlane_b32 s74, v254, 12
	v_readlane_b32 s75, v254, 13
	v_readlane_b32 s76, v254, 14
	v_readlane_b32 s77, v254, 15
	s_mov_b64 s[62:63], s[82:83]
	s_mov_b64 s[64:65], s[84:85]
	s_mov_b64 s[66:67], s[86:87]
	s_waitcnt vmcnt(1)
	v_cndmask_b32_e64 v98, v2, 0, s[0:1]
	v_cndmask_b32_e64 v99, v3, 0, s[0:1]
	v_lshl_add_u64 v[2:3], v[114:115], 2, v[10:11]
	global_load_dwordx4 v[66:69], v[2:3], off offset:16
	global_load_dwordx4 v[70:73], v[2:3], off
	v_lshl_add_u64 v[2:3], v[118:119], 0, s[28:29]
	v_cndmask_b32_e64 v96, v4, 0, s[0:1]
	v_cndmask_b32_e64 v97, v5, 0, s[0:1]
	v_lshl_add_u64 v[4:5], v[2:3], 0, s[6:7]
	global_load_dwordx4 v[34:37], v[4:5], off
	v_lshl_add_u64 v[4:5], v[2:3], 0, s[14:15]
	global_load_dwordx4 v[54:57], v[4:5], off
	s_add_i32 s14, s10, 16
	s_mov_b32 s15, s11
	s_lshl_b64 s[30:31], s[14:15], 10
	v_lshl_add_u64 v[4:5], v[2:3], 0, s[30:31]
	global_load_dwordx4 v[58:61], v[4:5], off
	s_add_i32 s14, s10, 24
	s_lshl_b64 s[14:15], s[14:15], 10
	v_lshl_add_u64 v[4:5], v[2:3], 0, s[14:15]
	global_load_dwordx4 v[62:65], v[4:5], off
	s_add_i32 s14, s10, 32
	s_mov_b32 s15, s11
	s_lshl_b64 s[34:35], s[14:15], 10
	v_lshl_add_u64 v[4:5], v[2:3], 0, s[34:35]
	global_load_dwordx4 v[74:77], v[4:5], off
	s_add_i32 s14, s10, 40
	s_lshl_b64 s[14:15], s[14:15], 10
	v_lshl_add_u64 v[4:5], v[2:3], 0, s[14:15]
	global_load_dwordx4 v[78:81], v[4:5], off
	s_add_i32 s14, s10, 48
	s_mov_b32 s15, s11
	s_lshl_b64 s[38:39], s[14:15], 10
	v_lshl_add_u64 v[4:5], v[2:3], 0, s[38:39]
	global_load_dwordx4 v[82:85], v[4:5], off
	s_add_i32 s14, s10, 56
	s_lshl_b64 s[14:15], s[14:15], 10
	v_lshl_add_u64 v[2:3], v[2:3], 0, s[14:15]
	global_load_dwordx4 v[86:89], v[2:3], off
	v_lshl_add_u64 v[2:3], v[120:121], 0, s[28:29]
	v_lshl_add_u64 v[4:5], v[2:3], 0, s[6:7]
	global_load_dwordx4 v[30:33], v[4:5], off
	v_lshl_add_u64 v[4:5], v[2:3], 0, s[30:31]
	global_load_dwordx4 v[22:25], v[4:5], off
	v_lshl_add_u64 v[4:5], v[2:3], 0, s[34:35]
	global_load_dwordx4 v[26:29], v[4:5], off
	v_lshl_add_u64 v[4:5], v[2:3], 0, s[38:39]
	s_lshl_b64 s[6:7], s[26:27], 10
	global_load_dwordx4 v[18:21], v[4:5], off
	v_lshl_add_u64 v[4:5], v[2:3], 0, s[6:7]
	s_sub_i32 s6, 31, s10
	s_ashr_i32 s7, s6, 31
	s_lshl_b64 s[6:7], s[6:7], 10
	global_load_dwordx4 v[14:17], v[4:5], off
	v_lshl_add_u64 v[4:5], v[2:3], 0, s[6:7]
	s_sub_i32 s6, 47, s10
	s_ashr_i32 s7, s6, 31
	s_lshl_b64 s[6:7], s[6:7], 10
	global_load_dwordx4 v[10:13], v[4:5], off
	v_lshl_add_u64 v[4:5], v[2:3], 0, s[6:7]
	s_sub_i32 s6, 63, s10
	s_ashr_i32 s7, s6, 31
	s_lshl_b64 s[6:7], s[6:7], 10
	v_lshl_add_u64 v[2:3], v[2:3], 0, s[6:7]
	s_waitcnt vmcnt(16)
	v_cndmask_b32_e64 v92, v8, 0, s[0:1]
	v_cndmask_b32_e64 v93, v9, 0, s[0:1]
	v_cndmask_b32_e64 v94, v6, 0, s[0:1]
	v_cndmask_b32_e64 v95, v7, 0, s[0:1]
	global_load_dwordx4 v[6:9], v[4:5], off
	s_and_b32 s27, s46, 0xffffffc0
	global_load_dwordx4 v[2:5], v[2:3], off
	s_lshl_b32 s6, s10, 2
	global_load_dwordx2 v[90:91], v[90:91], off
	ds_write_b128 v148, v[38:41]
	ds_write_b128 v149, v[42:45]
	ds_write_b128 v150, v[46:49]
	ds_write_b128 v151, v[50:53]
	v_cvt_pk_bf16_f32 v38, v98, v99
	v_cvt_pk_bf16_f32 v39, v96, v97
	v_cvt_pk_bf16_f32 v40, v94, v95
	v_cvt_pk_bf16_f32 v41, v92, v93
	ds_write_b128 v153, v[38:41]
	s_waitcnt vmcnt(17)
	v_cvt_pk_bf16_f32 v38, v70, v71
	v_cvt_pk_bf16_f32 v39, v72, v73
	v_cvt_pk_bf16_f32 v40, v66, v67
	v_cvt_pk_bf16_f32 v41, v68, v69
	ds_write_b128 v153, v[38:41] offset:8192
	s_waitcnt lgkmcnt(0)
	s_waitcnt lgkmcnt(0)
	s_barrier
	ds_read_b128 v[38:41], v154
	ds_read_b128 v[42:45], v154 offset:64
	s_waitcnt vmcnt(16) lgkmcnt(1)
	v_mfma_f32_16x16x32_bf16 v[38:41], v[34:37], v[38:41], 0
	v_add3_u32 v46, v141, s27, v142
	s_lshl_b64 s[14:15], s[8:9], 6
	s_mov_b32 s7, s11
	s_waitcnt vmcnt(15) lgkmcnt(0)
	v_mfma_f32_16x16x32_bf16 v[38:41], v[54:57], v[42:45], v[38:41]
	ds_read_b128 v[42:45], v154 offset:128
	s_mul_i32 s9, s10, 0x880
	s_or_b32 s28, s6, 1
	s_waitcnt vmcnt(14) lgkmcnt(0)
	v_mfma_f32_16x16x32_bf16 v[38:41], v[58:61], v[42:45], v[38:41]
	ds_read_b128 v[42:45], v154 offset:192
	s_mov_b32 s29, s11
	s_waitcnt vmcnt(13) lgkmcnt(0)
	v_mfma_f32_16x16x32_bf16 v[38:41], v[62:65], v[42:45], v[38:41]
	ds_read_b128 v[42:45], v154 offset:256
	s_waitcnt vmcnt(12) lgkmcnt(0)
	v_mfma_f32_16x16x32_bf16 v[38:41], v[74:77], v[42:45], v[38:41]
	ds_read_b128 v[42:45], v154 offset:320
	s_waitcnt vmcnt(11) lgkmcnt(0)
	v_mfma_f32_16x16x32_bf16 v[38:41], v[78:81], v[42:45], v[38:41]
	ds_read_b128 v[42:45], v154 offset:384
	s_waitcnt vmcnt(10) lgkmcnt(0)
	v_mfma_f32_16x16x32_bf16 v[38:41], v[82:85], v[42:45], v[38:41]
	ds_read_b128 v[42:45], v154 offset:448
	s_waitcnt vmcnt(9) lgkmcnt(0)
	v_mfma_f32_16x16x32_bf16 v[38:41], v[86:89], v[42:45], v[38:41]
	s_nop 7
	ds_write_b128 v46, v[38:41]
	ds_read_b128 v[38:41], v154 offset:8448
	ds_read_b128 v[42:45], v154 offset:8512
	s_waitcnt lgkmcnt(1)
	v_mfma_f32_16x16x32_bf16 v[38:41], v[34:37], v[38:41], 0
	s_waitcnt lgkmcnt(0)
	v_mfma_f32_16x16x32_bf16 v[38:41], v[54:57], v[42:45], v[38:41]
	ds_read_b128 v[42:45], v154 offset:8576
	s_waitcnt lgkmcnt(0)
	v_mfma_f32_16x16x32_bf16 v[38:41], v[58:61], v[42:45], v[38:41]
	ds_read_b128 v[42:45], v154 offset:8640
	s_waitcnt lgkmcnt(0)
	v_mfma_f32_16x16x32_bf16 v[38:41], v[62:65], v[42:45], v[38:41]
	ds_read_b128 v[42:45], v154 offset:8704
	s_waitcnt lgkmcnt(0)
	v_mfma_f32_16x16x32_bf16 v[38:41], v[74:77], v[42:45], v[38:41]
	ds_read_b128 v[42:45], v154 offset:8768
	s_waitcnt lgkmcnt(0)
	v_mfma_f32_16x16x32_bf16 v[38:41], v[78:81], v[42:45], v[38:41]
	ds_read_b128 v[42:45], v154 offset:8832
	s_waitcnt lgkmcnt(0)
	v_mfma_f32_16x16x32_bf16 v[38:41], v[82:85], v[42:45], v[38:41]
	ds_read_b128 v[42:45], v154 offset:8896
	s_waitcnt lgkmcnt(0)
	v_mfma_f32_16x16x32_bf16 v[38:41], v[86:89], v[42:45], v[38:41]
	s_nop 7
	ds_write_b128 v46, v[38:41] offset:8448
	ds_read_b128 v[38:41], v154 offset:16896
	ds_read_b128 v[42:45], v154 offset:16960
	s_waitcnt lgkmcnt(1)
	v_mfma_f32_16x16x32_bf16 v[38:41], v[34:37], v[38:41], 0
	s_waitcnt lgkmcnt(0)
	v_mfma_f32_16x16x32_bf16 v[38:41], v[54:57], v[42:45], v[38:41]
	ds_read_b128 v[42:45], v154 offset:17024
	s_waitcnt lgkmcnt(0)
	v_mfma_f32_16x16x32_bf16 v[38:41], v[58:61], v[42:45], v[38:41]
	ds_read_b128 v[42:45], v154 offset:17088
	s_waitcnt lgkmcnt(0)
	v_mfma_f32_16x16x32_bf16 v[38:41], v[62:65], v[42:45], v[38:41]
	ds_read_b128 v[42:45], v154 offset:17152
	s_waitcnt lgkmcnt(0)
	v_mfma_f32_16x16x32_bf16 v[38:41], v[74:77], v[42:45], v[38:41]
	ds_read_b128 v[42:45], v154 offset:17216
	s_waitcnt lgkmcnt(0)
	v_mfma_f32_16x16x32_bf16 v[38:41], v[78:81], v[42:45], v[38:41]
	ds_read_b128 v[42:45], v154 offset:17280
	s_waitcnt lgkmcnt(0)
	v_mfma_f32_16x16x32_bf16 v[38:41], v[82:85], v[42:45], v[38:41]
	ds_read_b128 v[42:45], v154 offset:17344
	s_waitcnt lgkmcnt(0)
	v_mfma_f32_16x16x32_bf16 v[38:41], v[86:89], v[42:45], v[38:41]
	s_nop 7
	ds_write_b128 v46, v[38:41] offset:16896
	ds_read_b128 v[38:41], v154 offset:25344
	s_waitcnt lgkmcnt(0)
	v_mfma_f32_16x16x32_bf16 v[34:37], v[34:37], v[38:41], 0
	ds_read_b128 v[38:41], v154 offset:25408
	s_waitcnt lgkmcnt(0)
	v_mfma_f32_16x16x32_bf16 v[34:37], v[54:57], v[38:41], v[34:37]
	ds_read_b128 v[38:41], v154 offset:25472
	s_waitcnt lgkmcnt(0)
	v_mfma_f32_16x16x32_bf16 v[34:37], v[58:61], v[38:41], v[34:37]
	ds_read_b128 v[38:41], v154 offset:25536
	s_waitcnt lgkmcnt(0)
	v_mfma_f32_16x16x32_bf16 v[34:37], v[62:65], v[38:41], v[34:37]
	ds_read_b128 v[38:41], v154 offset:25600
	s_waitcnt lgkmcnt(0)
	v_mfma_f32_16x16x32_bf16 v[34:37], v[74:77], v[38:41], v[34:37]
	ds_read_b128 v[38:41], v154 offset:25664
	s_waitcnt lgkmcnt(0)
	v_mfma_f32_16x16x32_bf16 v[34:37], v[78:81], v[38:41], v[34:37]
	ds_read_b128 v[38:41], v154 offset:25728
	s_waitcnt lgkmcnt(0)
	v_mfma_f32_16x16x32_bf16 v[34:37], v[82:85], v[38:41], v[34:37]
	ds_read_b128 v[38:41], v154 offset:25792
	s_waitcnt lgkmcnt(0)
	v_mfma_f32_16x16x32_bf16 v[34:37], v[86:89], v[38:41], v[34:37]
	s_nop 7
	ds_write_b128 v46, v[34:37] offset:25344
	v_mov_b32_e32 v35, s15
	v_or_b32_e32 v34, s14, v186
	s_lshl_b64 s[14:15], s[6:7], 12
	v_lshl_add_u64 v[36:37], s[14:15], 0, v[34:35]
	v_lshlrev_b64 v[36:37], 2, v[36:37]
	s_waitcnt lgkmcnt(0)
	s_barrier
	v_lshl_add_u64 v[38:39], s[58:59], 0, v[36:37]
	global_load_dword v40, v[38:39], off
	v_lshl_add_u64 v[38:39], s[60:61], 0, v[36:37]
	global_load_dword v41, v[38:39], off
	s_waitcnt vmcnt(1)
	v_cvt_pk_bf16_f32 v38, v40, v115
	v_add_u32_e32 v39, s9, v146
	ds_write_b16 v39, v38
	s_waitcnt vmcnt(0)
	v_cvt_pk_bf16_f32 v38, v41, v115
	s_mul_i32 s9, s10, 0x1080
	ds_write_b16 v39, v38 offset:128
	v_add_u32_e32 v38, s9, v147
	ds_read2st64_b32 v[38:39], v38 offset1:1
	s_lshl_b32 s7, s10, 3
	s_or_b32 s7, s7, 1
	s_mul_i32 s9, s7, 0x110
	s_mulk_i32 s7, 0x210
	v_lshl_add_u64 v[36:37], s[68:69], 0, v[36:37]
	s_lshl_b64 s[14:15], s[28:29], 12
	s_waitcnt lgkmcnt(0)
	v_fmac_f32_e32 v39, v91, v40
	v_fma_f32 v38, -v91, v41, v38
	v_fmac_f32_e32 v38, v90, v40
	v_fmac_f32_e32 v39, v90, v41
	v_cvt_pk_bf16_f32 v40, v38, v115
	v_add_u32_e32 v41, s9, v146
	ds_write_b16 v41, v40
	v_cvt_pk_bf16_f32 v40, v39, v115
	ds_write_b16 v41, v40 offset:128
	v_add_u32_e32 v40, s7, v147
	ds_read2st64_b32 v[40:41], v40 offset1:1
	s_mul_i32 s9, s28, 0x220
	s_lshl_b32 s7, s28, 1
	s_or_b32 s7, s7, 1
	s_waitcnt lgkmcnt(0)
	v_fma_f32 v40, -v91, v39, v40
	v_fmac_f32_e32 v40, v90, v38
	v_fmac_f32_e32 v41, v91, v38
	v_add_co_u32_e32 v38, vcc, s41, v36
	v_fmac_f32_e32 v41, v90, v39
	s_nop 0
	v_addc_co_u32_e32 v39, vcc, 0, v37, vcc
	v_add_co_u32_e32 v36, vcc, s44, v36
	global_store_dword v[38:39], v40, off
	s_nop 0
	v_addc_co_u32_e32 v37, vcc, 0, v37, vcc
	global_store_dword v[36:37], v41, off
	v_lshl_add_u64 v[36:37], s[14:15], 0, v[34:35]
	v_lshlrev_b64 v[38:39], 2, v[36:37]
	v_lshl_add_u64 v[36:37], s[58:59], 0, v[38:39]
	global_load_dword v42, v[36:37], off
	v_lshl_add_u64 v[36:37], s[60:61], 0, v[38:39]
	global_load_dword v43, v[36:37], off
	s_waitcnt vmcnt(1)
	v_cvt_pk_bf16_f32 v37, v42, v115
	v_add_u32_e32 v36, s9, v146
	ds_write_b16 v36, v37
	s_waitcnt vmcnt(0)
	v_cvt_pk_bf16_f32 v37, v43, v115
	s_mul_i32 s9, s28, 0x420
	ds_write_b16 v36, v37 offset:128
	v_add_u32_e32 v37, s9, v147
	ds_read2st64_b32 v[40:41], v37 offset1:1
	s_mul_i32 s9, s7, 0x110
	s_mulk_i32 s7, 0x210
	v_lshl_add_u64 v[38:39], s[68:69], 0, v[38:39]
	s_or_b32 s28, s6, 2
	s_lshl_b64 s[14:15], s[28:29], 12
	s_or_b32 s6, s6, 3
	s_waitcnt lgkmcnt(0)
	v_fmac_f32_e32 v41, v91, v42
	v_fma_f32 v40, -v91, v43, v40
	v_fmac_f32_e32 v40, v90, v42
	v_fmac_f32_e32 v41, v90, v43
	v_cvt_pk_bf16_f32 v42, v40, v115
	v_add_u32_e32 v43, s9, v146
	ds_write_b16 v43, v42
	v_cvt_pk_bf16_f32 v42, v41, v115
	ds_write_b16 v43, v42 offset:128
	v_add_u32_e32 v42, s7, v147
	ds_read2st64_b32 v[42:43], v42 offset1:1
	s_lshl_b32 s7, s28, 1
	s_or_b32 s7, s7, 1
	s_mul_i32 s9, s7, 0x110
	s_mulk_i32 s7, 0x210
	s_waitcnt lgkmcnt(0)
	v_fma_f32 v42, -v91, v41, v42
	v_fmac_f32_e32 v42, v90, v40
	v_fmac_f32_e32 v43, v91, v40
	v_add_co_u32_e32 v40, vcc, s41, v38
	v_fmac_f32_e32 v43, v90, v41
	s_nop 0
	v_addc_co_u32_e32 v41, vcc, 0, v39, vcc
	v_add_co_u32_e32 v38, vcc, s44, v38
	global_store_dword v[40:41], v42, off
	s_nop 0
	v_addc_co_u32_e32 v39, vcc, 0, v39, vcc
	global_store_dword v[38:39], v43, off
	v_lshl_add_u64 v[38:39], s[14:15], 0, v[34:35]
	v_lshlrev_b64 v[38:39], 2, v[38:39]
	v_lshl_add_u64 v[40:41], s[58:59], 0, v[38:39]
	global_load_dword v42, v[40:41], off
	v_lshl_add_u64 v[40:41], s[60:61], 0, v[38:39]
	global_load_dword v43, v[40:41], off
	s_waitcnt vmcnt(1)
	v_cvt_pk_bf16_f32 v40, v42, v115
	ds_write_b16 v36, v40 offset:544
	s_waitcnt vmcnt(0)
	v_cvt_pk_bf16_f32 v40, v43, v115
	ds_write_b16 v36, v40 offset:672
	v_add_u32_e32 v40, 32, v37
	ds_read2st64_b32 v[40:41], v40 offset0:4 offset1:5
	v_lshl_add_u64 v[38:39], s[68:69], 0, v[38:39]
	s_waitcnt lgkmcnt(0)
	v_fmac_f32_e32 v41, v91, v42
	v_fma_f32 v40, -v91, v43, v40
	v_fmac_f32_e32 v40, v90, v42
	v_fmac_f32_e32 v41, v90, v43
	v_cvt_pk_bf16_f32 v42, v40, v115
	v_add_u32_e32 v43, s9, v146
	ds_write_b16 v43, v42
	v_cvt_pk_bf16_f32 v42, v41, v115
	ds_write_b16 v43, v42 offset:128
	v_add_u32_e32 v42, s7, v147
	ds_read2st64_b32 v[42:43], v42 offset1:1
	s_mov_b32 s7, s11
	s_lshl_b64 s[14:15], s[6:7], 12
	v_lshl_add_u64 v[34:35], s[14:15], 0, v[34:35]
	v_lshlrev_b64 v[34:35], 2, v[34:35]
	s_waitcnt lgkmcnt(0)
	v_fma_f32 v42, -v91, v41, v42
	v_fmac_f32_e32 v42, v90, v40
	v_fmac_f32_e32 v43, v91, v40
	v_add_co_u32_e32 v40, vcc, s41, v38
	v_fmac_f32_e32 v43, v90, v41
	s_nop 0
	v_addc_co_u32_e32 v41, vcc, 0, v39, vcc
	v_add_co_u32_e32 v38, vcc, s44, v38
	global_store_dword v[40:41], v42, off
	s_nop 0
	v_addc_co_u32_e32 v39, vcc, 0, v39, vcc
	global_store_dword v[38:39], v43, off
	v_lshl_add_u64 v[38:39], s[58:59], 0, v[34:35]
	global_load_dword v40, v[38:39], off
	v_lshl_add_u64 v[38:39], s[60:61], 0, v[34:35]
	global_load_dword v38, v[38:39], off
	s_waitcnt vmcnt(1)
	v_cvt_pk_bf16_f32 v39, v40, v115
	ds_write_b16 v36, v39 offset:1088
	s_waitcnt vmcnt(0)
	v_cvt_pk_bf16_f32 v39, v38, v115
	ds_write_b16 v36, v39 offset:1216
	v_add_u32_e32 v36, 64, v37
	ds_read2st64_b32 v[36:37], v36 offset0:8 offset1:9
	s_lshl_b32 s6, s6, 1
	s_or_b32 s6, s6, 1
	s_mul_i32 s7, s6, 0x110
	v_add_u32_e32 v39, s7, v146
	s_mulk_i32 s6, 0x210
	v_lshl_add_u64 v[34:35], s[68:69], 0, v[34:35]
	s_waitcnt lgkmcnt(0)
	v_fmac_f32_e32 v37, v91, v40
	v_fma_f32 v36, -v91, v38, v36
	v_fmac_f32_e32 v36, v90, v40
	v_fmac_f32_e32 v37, v90, v38
	v_cvt_pk_bf16_f32 v38, v36, v115
	ds_write_b16 v39, v38
	v_cvt_pk_bf16_f32 v38, v37, v115
	ds_write_b16 v39, v38 offset:128
	v_add_u32_e32 v38, s6, v147
	ds_read2st64_b32 v[38:39], v38 offset1:1
	s_lshr_b32 s6, s46, 7
	s_waitcnt lgkmcnt(0)
	v_fma_f32 v38, -v91, v37, v38
	v_fmac_f32_e32 v38, v90, v36
	v_fmac_f32_e32 v39, v91, v36
	v_add_co_u32_e32 v36, vcc, s41, v34
	v_fmac_f32_e32 v39, v90, v37
	s_nop 0
	v_addc_co_u32_e32 v37, vcc, 0, v35, vcc
	v_add_co_u32_e32 v34, vcc, s44, v34
	global_store_dword v[36:37], v38, off
	s_nop 0
	v_addc_co_u32_e32 v35, vcc, 0, v35, vcc
	global_store_dword v[34:35], v39, off
	s_waitcnt lgkmcnt(0)
	s_barrier
	ds_read_b128 v[46:49], v152
	ds_read_b128 v[74:77], v152 offset:128
	ds_read_b128 v[42:45], v152 offset:4352
	ds_read_b128 v[38:41], v152 offset:8704
	ds_read_b128 v[34:37], v152 offset:13056
	s_waitcnt lgkmcnt(4)
	v_mfma_f32_16x16x32_bf16 v[50:53], v[30:33], v[46:49], 0
	ds_read_b128 v[70:73], v152 offset:4480
	ds_read_b128 v[90:93], v152 offset:8896
	s_waitcnt lgkmcnt(4)
	v_mfma_f32_16x16x32_bf16 v[54:57], v[30:33], v[42:45], 0
	s_waitcnt lgkmcnt(3)
	v_mfma_f32_16x16x32_bf16 v[58:61], v[30:33], v[38:41], 0
	s_waitcnt lgkmcnt(2)
	v_mfma_f32_16x16x32_bf16 v[62:65], v[30:33], v[34:37], 0
	ds_read_b128 v[30:33], v152 offset:64
	s_waitcnt lgkmcnt(0)
	v_mfma_f32_16x16x32_bf16 v[66:69], v[22:25], v[30:33], v[50:53]
	s_nop 2
	ds_read_b128 v[50:53], v152 offset:4416
	v_mfma_f32_16x16x32_bf16 v[86:89], v[26:29], v[74:77], v[66:69]
	s_nop 2
	ds_read_b128 v[66:69], v152 offset:8832
	s_waitcnt lgkmcnt(1)
	v_mfma_f32_16x16x32_bf16 v[78:81], v[22:25], v[50:53], v[54:57]
	s_nop 2
	ds_read_b128 v[54:57], v152 offset:8768
	s_waitcnt lgkmcnt(0)
	v_mfma_f32_16x16x32_bf16 v[82:85], v[22:25], v[54:57], v[58:61]
	s_nop 2
	ds_read_b128 v[58:61], v152 offset:13120
	s_waitcnt lgkmcnt(0)
	v_mfma_f32_16x16x32_bf16 v[22:25], v[22:25], v[58:61], v[62:65]
	s_nop 2
	ds_read_b128 v[62:65], v152 offset:13184
	v_mfma_f32_16x16x32_bf16 v[94:97], v[26:29], v[66:69], v[82:85]
	s_nop 2
	ds_read_b128 v[82:85], v152 offset:192
	v_mfma_f32_16x16x32_bf16 v[78:81], v[26:29], v[70:73], v[78:81]
	s_waitcnt lgkmcnt(1)
	v_mfma_f32_16x16x32_bf16 v[98:101], v[26:29], v[62:65], v[22:25]
	s_waitcnt lgkmcnt(0)
	v_mfma_f32_16x16x32_bf16 v[26:29], v[18:21], v[82:85], v[86:89]
	s_nop 2
	ds_read_b128 v[86:89], v152 offset:4544
	v_mfma_f32_16x16x32_bf16 v[22:25], v[18:21], v[90:93], v[94:97]
	s_nop 2
	ds_read_b128 v[94:97], v152 offset:13248
	s_waitcnt lgkmcnt(1)
	v_mfma_f32_16x16x32_bf16 v[78:81], v[18:21], v[86:89], v[78:81]
	s_waitcnt lgkmcnt(0)
	v_mfma_f32_16x16x32_bf16 v[18:21], v[18:21], v[94:97], v[98:101]
	ds_read_b128 v[110:113], v154
	ds_read_b128 v[106:109], v154 offset:8448
	ds_read_b128 v[102:105], v154 offset:16896
	ds_read_b128 v[98:101], v154 offset:25344
	ds_read_b128 v[156:159], v155
.LBB0_1024:
	s_add_i32 s7, s45, 1
	s_cmp_lt_u32 s45, s6
	s_cselect_b32 s9, s7, s45
	s_lshl_b32 s14, s9, 7
	s_lshl_b32 s9, s9, 6
	v_add3_u32 v155, v140, s9, v142
	s_sub_i32 s14, s27, s14
	v_or_b32_e32 v168, s14, v186
	v_lshl_add_u32 v246, v168, 4, s40
	ds_read_b128 v[242:245], v246
	s_waitcnt lgkmcnt(1)
	v_mfma_f32_16x16x32_bf16 v[26:29], v[156:159], v[110:113], v[26:29]
	ds_read_b128 v[110:113], v155
	s_cmp_eq_u32 s45, s6
	s_mov_b32 s45, s7
	v_mfma_f32_16x16x32_bf16 v[78:81], v[156:159], v[106:109], v[78:81]
	ds_read_b128 v[106:109], v155 offset:8448
	ds_read_b128 v[160:163], v155 offset:16896
	ds_read_b128 v[164:167], v155 offset:25344
	v_mfma_f32_16x16x32_bf16 v[22:25], v[156:159], v[102:105], v[22:25]
	s_waitcnt lgkmcnt(1)
	v_mov_b32_e32 v102, v160
	v_mov_b32_e32 v103, v161
	v_mov_b32_e32 v104, v162
	v_mfma_f32_16x16x32_bf16 v[18:21], v[156:159], v[98:101], v[18:21]
	s_waitcnt lgkmcnt(0)
	v_mov_b64_e32 v[98:99], v[164:165]
	v_mov_b64_e32 v[100:101], v[166:167]
	v_mov_b32_e32 v105, v163
	v_mov_b64_e32 v[156:157], v[242:243]
	v_mov_b64_e32 v[158:159], v[244:245]
	s_cbranch_scc0 .LBB0_1024
	v_mfma_f32_16x16x32_bf16 v[46:49], v[14:17], v[46:49], 0
	v_mul_f32_e64 v100, v26, s24
	v_mul_f32_e64 v101, v27, s24
	v_pk_mul_f32 v[104:105], v[78:79], s[24:25] op_sel_hi:[1,0]
	v_pk_fma_f32 v[100:101], v[26:27], v[100:101], 1.0 op_sel_hi:[1,1,0]
	v_mfma_f32_16x16x32_bf16 v[42:45], v[14:17], v[42:45], 0
	v_mul_f32_e64 v100, v26, v100
	v_mul_f32_e64 v101, v27, v101
	v_pk_fma_f32 v[104:105], v[78:79], v[104:105], 1.0 op_sel_hi:[1,1,0]
	v_pk_mul_f32 v[98:99], v[28:29], s[24:25] op_sel_hi:[1,0]
	v_mfma_f32_16x16x32_bf16 v[38:41], v[14:17], v[38:41], 0
	v_mul_f32_e64 v104, v78, v104
	v_mul_f32_e64 v105, v79, v105
	v_pk_mul_f32 v[102:103], v[80:81], s[24:25] op_sel_hi:[1,0]
	v_pk_fma_f32 v[98:99], v[28:29], v[98:99], 1.0 op_sel_hi:[1,1,0]
	v_mfma_f32_16x16x32_bf16 v[14:17], v[14:17], v[34:37], 0
	v_mul_f32_e32 v34, 0xc0135761, v100
	v_pk_fma_f32 v[102:103], v[80:81], v[102:103], 1.0 op_sel_hi:[1,1,0]
	v_pk_mul_f32 v[98:99], v[28:29], v[98:99]
	v_mfma_f32_16x16x32_bf16 v[30:33], v[10:13], v[30:33], v[46:49]
	v_mul_f32_e64 v102, v80, v102
	v_mul_f32_e64 v103, v81, v103
	s_lshl_b32 s6, s10, 5
	v_exp_f32_e32 v46, v34
	v_mul_f32_e32 v34, 0xc0135761, v104
	v_exp_f32_e32 v47, v34
	v_mfma_f32_16x16x32_bf16 v[34:37], v[10:13], v[50:53], v[42:45]
	s_nop 2
	v_mul_f32_e32 v42, 0xc0135761, v101
	v_exp_f32_e32 v43, v42
	v_mul_f32_e32 v42, 0xc0135761, v105
	v_mfma_f32_16x16x32_bf16 v[38:41], v[10:13], v[54:57], v[38:41]
	v_exp_f32_e32 v45, v42
	v_mul_f32_e32 v42, 0xc0135761, v98
	v_exp_f32_e32 v48, v42
	v_mfma_f32_16x16x32_bf16 v[10:13], v[10:13], v[58:61], v[14:17]
	v_mul_f32_e32 v42, 0xc0135761, v99
	v_exp_f32_e32 v50, v42
	v_add_f32_e32 v44, 1.0, v47
	v_mul_f32_e32 v14, 0xc0135761, v102
	v_exp_f32_e32 v49, v14
	v_mfma_f32_16x16x32_bf16 v[14:17], v[6:9], v[74:77], v[30:33]
	v_rcp_f32_e32 v44, v44
	s_nop 1
	v_mul_f32_e32 v30, 0xc0135761, v103
	v_exp_f32_e32 v51, v30
	v_mfma_f32_16x16x32_bf16 v[30:33], v[6:9], v[70:73], v[34:37]
	s_nop 2
	v_add_f32_e32 v34, 1.0, v46
	v_rcp_f32_e32 v42, v34
	v_mfma_f32_16x16x32_bf16 v[34:37], v[6:9], v[66:69], v[38:41]
	s_nop 2
	v_add_f32_e32 v38, 1.0, v43
	v_rcp_f32_e32 v43, v38
	v_mfma_f32_16x16x32_bf16 v[38:41], v[6:9], v[62:65], v[10:13]
	v_add_f32_e32 v6, 1.0, v45
	v_rcp_f32_e32 v45, v6
	v_add_f32_e32 v6, 1.0, v48
	v_rcp_f32_e32 v46, v6
	v_add_f32_e32 v6, 1.0, v49
	v_rcp_f32_e32 v48, v6
	v_add_f32_e32 v6, 1.0, v50
	v_mfma_f32_16x16x32_bf16 v[10:13], v[2:5], v[86:89], v[30:33]
	v_rcp_f32_e32 v47, v6
	v_pk_mul_f32 v[26:27], v[26:27], v[42:43]
	v_pk_mul_f32 v[28:29], v[28:29], v[46:47]
	v_add_f32_e32 v30, 1.0, v51
	v_rcp_f32_e32 v49, v30
	v_mfma_f32_16x16x32_bf16 v[6:9], v[2:5], v[90:93], v[34:37]
	v_cvt_pk_bf16_f32 v26, v26, v27
	v_cvt_pk_bf16_f32 v27, v28, v29
	v_mul_f32_e64 v30, v80, v48
	v_mul_f32_e64 v31, v81, v49
	v_pk_mul_f32 v[32:33], v[78:79], v[44:45]
	v_mfma_f32_16x16x32_bf16 v[14:17], v[2:5], v[82:85], v[14:17]
	v_add3_u32 v34, v144, s6, v142
	v_cvt_pk_bf16_f32 v28, v32, v33
	v_cvt_pk_bf16_f32 v29, v30, v31
	ds_write_b64 v34, v[26:27]
	ds_write_b64 v34, v[28:29] offset:8448
	v_pk_mul_f32 v[26:27], v[24:25], s[24:25] op_sel_hi:[1,0]
	v_pk_mul_f32 v[30:31], v[20:21], s[24:25] op_sel_hi:[1,0]
	v_pk_fma_f32 v[26:27], v[24:25], v[26:27], 1.0 op_sel_hi:[1,1,0]
	v_pk_mul_f32 v[32:33], v[18:19], s[24:25] op_sel_hi:[1,0]
	v_pk_mul_f32 v[28:29], v[22:23], s[24:25] op_sel_hi:[1,0]
	v_pk_mul_f32 v[26:27], v[24:25], v[26:27]
	v_pk_fma_f32 v[30:31], v[20:21], v[30:31], 1.0 op_sel_hi:[1,1,0]
	v_pk_fma_f32 v[32:33], v[18:19], v[32:33], 1.0 op_sel_hi:[1,1,0]
	v_pk_fma_f32 v[28:29], v[22:23], v[28:29], 1.0 op_sel_hi:[1,1,0]
	v_pk_mul_f32 v[30:31], v[20:21], v[30:31]
	v_pk_mul_f32 v[32:33], v[18:19], v[32:33]
	v_mul_f32_e32 v26, 0xc0135761, v26
	v_pk_mul_f32 v[28:29], v[22:23], v[28:29]
	v_mul_f32_e32 v32, 0xc0135761, v32
	v_exp_f32_e32 v35, v26
	v_mul_f32_e32 v26, 0xc0135761, v30
	v_mul_f32_e32 v28, 0xc0135761, v28
	v_exp_f32_e32 v32, v32
	v_mul_f32_e32 v29, 0xc0135761, v29
	v_mul_f32_e32 v33, 0xc0135761, v33
	v_exp_f32_e32 v36, v26
	v_mul_f32_e32 v26, 0xc0135761, v27
	v_exp_f32_e32 v28, v28
	v_exp_f32_e32 v29, v29
	v_exp_f32_e32 v33, v33
	v_exp_f32_e32 v37, v26
	v_mul_f32_e32 v26, 0xc0135761, v31
	v_mfma_f32_16x16x32_bf16 v[2:5], v[2:5], v[94:97], v[38:41]
	v_add_f32_e32 v27, 1.0, v32
	v_add_f32_e32 v31, 1.0, v36
	v_add_f32_e32 v30, 1.0, v35
	v_exp_f32_e32 v38, v26
	v_add_f32_e32 v26, 1.0, v28
	v_rcp_f32_e32 v28, v27
	v_add_f32_e32 v27, 1.0, v29
	v_add_f32_e32 v29, 1.0, v33
	v_rcp_f32_e32 v26, v26
	v_rcp_f32_e32 v27, v27
	v_rcp_f32_e32 v32, v31
	v_add_f32_e32 v31, 1.0, v37
	v_add_f32_e32 v33, 1.0, v38
	v_rcp_f32_e32 v29, v29
	v_rcp_f32_e32 v30, v30
	v_rcp_f32_e32 v31, v31
	v_rcp_f32_e32 v33, v33
	s_ashr_i32 s6, s26, 1
	v_pk_mul_f32 v[22:23], v[22:23], v[26:27]
	v_pk_mul_f32 v[18:19], v[18:19], v[28:29]
	s_cmp_gt_i32 s6, -1
	v_pk_mul_f32 v[24:25], v[24:25], v[30:31]
	v_pk_mul_f32 v[20:21], v[20:21], v[32:33]
	v_cvt_pk_bf16_f32 v22, v22, v23
	v_cvt_pk_bf16_f32 v23, v24, v25
	v_cvt_pk_bf16_f32 v18, v18, v19
	s_nop 0
	v_cvt_pk_bf16_f32 v19, v20, v21
	ds_write_b64 v34, v[22:23] offset:16896
	ds_write_b64 v34, v[18:19] offset:25344
	s_cbranch_scc0 .LBB0_1022
	ds_read_b128 v[30:33], v154
	ds_read_b128 v[26:29], v154 offset:8448
	ds_read_b128 v[22:25], v154 offset:16896
	ds_read_b128 v[18:21], v154 offset:25344
	v_lshl_add_u32 v34, s26, 10, v143
	s_lshl_b32 s7, s26, 6
	s_mov_b32 s9, 0
	ds_read_b128 v[36:39], v34
.LBB0_1027:
	s_add_i32 s10, s9, 1
	s_cmp_lt_i32 s9, s6
	s_cselect_b32 s14, s10, s9
	s_lshl_b32 s15, s14, 7
	s_lshl_b32 s14, s14, 6
	v_add3_u32 v34, v140, s14, v142
	s_sub_i32 s15, s7, s15
	v_or_b32_e32 v35, s15, v186
	v_lshl_add_u32 v246, v35, 4, s40
	ds_read_b128 v[242:245], v246
	s_waitcnt lgkmcnt(1)
	v_mfma_f32_16x16x32_bf16 v[14:17], v[36:39], v[30:33], v[14:17]
	ds_read_b128 v[30:33], v34
	s_cmp_lg_u32 s9, s6
	s_mov_b32 s9, s10
	v_mfma_f32_16x16x32_bf16 v[10:13], v[36:39], v[26:29], v[10:13]
	ds_read_b128 v[26:29], v34 offset:8448
	ds_read_b128 v[40:43], v34 offset:16896
	ds_read_b128 v[44:47], v34 offset:25344
	v_mfma_f32_16x16x32_bf16 v[6:9], v[36:39], v[22:25], v[6:9]
	s_waitcnt lgkmcnt(1)
	v_mov_b32_e32 v22, v40
	v_mov_b32_e32 v23, v41
	v_mov_b32_e32 v24, v42
	v_mfma_f32_16x16x32_bf16 v[2:5], v[36:39], v[18:21], v[2:5]
	s_waitcnt lgkmcnt(0)
	v_mov_b64_e32 v[18:19], v[44:45]
	v_mov_b64_e32 v[20:21], v[46:47]
	v_mov_b32_e32 v25, v43
	v_mov_b64_e32 v[36:37], v[242:243]
	v_mov_b64_e32 v[38:39], v[244:245]
	s_cbranch_scc1 .LBB0_1027
	s_branch .LBB0_1022
